# attention epilogue: half-wave exchange (v_permlane32_swap) so each lane stores 16 contiguous bytes, 8 dwordx4 instead of 16 dwordx2 per wave
# speedup vs baseline: 1.0222x; 1.0010x over previous
; __device__ __forceinline__ unsigned cvt_pk_bf16(float lo, float hi) { unsigned r; asm volatile("v_cvt_pk_bf16_f32 %0, %1, %2" : "=v"(r) : "v"(lo), "v"(hi)); return r; }
; __device__ __forceinline__ float xor_lane(float v, int lane, int mask) { return __int_as_float(__builtin_amdgcn_ds_bpermute((lane ^ mask) << 2, __float_as_int(v))); }
; __device__ __forceinline__ void attn_unit(LAS unsigned char* lds, const bf16_t* Q, const bf16_t* Kb, const bf16_t* Vb, bf16_t* O, const float* sink,
;                                           int qrow0, int kvh, int crow0, int lrow0, int jlo, int jhi, int qpos0, const int wave_s) {
;     ...
; #pragma unroll
;     for (int qs = 0; qs < 2; ++qs) {
;         const float lt = lsum[qs] + xor_lane(lsum[qs], lane, 32);
;         const float inv = 1.0f / lt;
;         bf16_t* orow = O + (size_t)(qrow0 + 32 * qs + l31) * D + head * 64;
; #pragma unroll
;         for (int dh = 0; dh < 2; ++dh)
; #pragma unroll
;             for (int rg = 0; rg < 4; ++rg) {
;                 u32x2 w; w.x = cvt_pk_bf16(Oacc[qs][dh][4 * rg + 0] * inv, Oacc[qs][dh][4 * rg + 1] * inv); w.y = cvt_pk_bf16(Oacc[qs][dh][4 * rg + 2] * inv, Oacc[qs][dh][4 * rg + 3] * inv);
;                 *(u32x2*)(orow + 32 * dh + 8 * rg + 4 * h) = w;
;             }
;     }
.LBB0_337:
	ds_bpermute_b32 v65, v187, v80
	s_add_u32 s8, s46, s10
	s_addc_u32 s9, s47, s11
	v_lshlrev_b32_e32 v176, 1, v195
	v_lshl_add_u64 v[66:67], s[8:9], 0, v[176:177]
	s_waitcnt lgkmcnt(0)
	v_add_f32_e32 v65, v80, v65
	v_div_scale_f32 v68, s[8:9], v65, v65, 1.0
	v_rcp_f32_e32 v69, v68
	s_nop 0
	v_fma_f32 v70, -v68, v69, 1.0
	v_fmac_f32_e32 v69, v70, v69
	v_div_scale_f32 v70, vcc, 1.0, v65, 1.0
	v_mul_f32_e32 v71, v70, v69
	v_fma_f32 v72, -v68, v71, v70
	v_fmac_f32_e32 v71, v72, v69
	v_fma_f32 v68, -v68, v71, v70
	v_div_fmas_f32 v68, v68, v69, v71
	v_div_fixup_f32 v65, v68, v65, 1.0
	v_lshl_add_u64 v[68:69], v[66:67], 0, v[170:171]
	v_lshl_add_u64 v[68:69], v[68:69], 0, v[176:177]
	v_mul_f32_e32 v152, v0, v65
	v_mul_f32_e32 v153, v1, v65
	v_mul_f32_e32 v154, v2, v65
	v_mul_f32_e32 v155, v3, v65
	v_mul_f32_e32 v156, v4, v65
	v_mul_f32_e32 v157, v5, v65
	v_mul_f32_e32 v158, v6, v65
	v_mul_f32_e32 v159, v7, v65
	v_cvt_pk_bf16_f32 v136, v152, v153
	v_cvt_pk_bf16_f32 v137, v154, v155
	v_cvt_pk_bf16_f32 v138, v156, v157
	v_cvt_pk_bf16_f32 v139, v158, v159
	s_nop 1
	v_permlane32_swap_b32_e32 v136, v138
	v_permlane32_swap_b32_e32 v137, v139
	global_store_dwordx4 v[68:69], v[136:139], off
	v_mul_f32_e32 v152, v8, v65
	v_mul_f32_e32 v153, v9, v65
	v_mul_f32_e32 v154, v10, v65
	v_mul_f32_e32 v155, v11, v65
	v_mul_f32_e32 v156, v12, v65
	v_mul_f32_e32 v157, v13, v65
	v_mul_f32_e32 v158, v14, v65
	v_mul_f32_e32 v159, v15, v65
	v_cvt_pk_bf16_f32 v140, v152, v153
	v_cvt_pk_bf16_f32 v141, v154, v155
	v_cvt_pk_bf16_f32 v142, v156, v157
	v_cvt_pk_bf16_f32 v143, v158, v159
	s_nop 1
	v_permlane32_swap_b32_e32 v140, v142
	v_permlane32_swap_b32_e32 v141, v143
	global_store_dwordx4 v[68:69], v[140:143], off offset:32
	v_mul_f32_e32 v152, v48, v65
	v_mul_f32_e32 v153, v49, v65
	v_mul_f32_e32 v154, v50, v65
	v_mul_f32_e32 v155, v51, v65
	v_mul_f32_e32 v156, v52, v65
	v_mul_f32_e32 v157, v53, v65
	v_mul_f32_e32 v158, v54, v65
	v_mul_f32_e32 v159, v55, v65
	v_cvt_pk_bf16_f32 v144, v152, v153
	v_cvt_pk_bf16_f32 v145, v154, v155
	v_cvt_pk_bf16_f32 v146, v156, v157
	v_cvt_pk_bf16_f32 v147, v158, v159
	s_nop 1
	v_permlane32_swap_b32_e32 v144, v146
	v_permlane32_swap_b32_e32 v145, v147
	global_store_dwordx4 v[68:69], v[144:147], off offset:64
	v_mul_f32_e32 v152, v56, v65
	v_mul_f32_e32 v153, v57, v65
	v_mul_f32_e32 v154, v58, v65
	v_mul_f32_e32 v155, v59, v65
	v_mul_f32_e32 v156, v60, v65
	v_mul_f32_e32 v157, v61, v65
	v_mul_f32_e32 v158, v62, v65
	v_mul_f32_e32 v159, v63, v65
	v_cvt_pk_bf16_f32 v148, v152, v153
	v_cvt_pk_bf16_f32 v149, v154, v155
	v_cvt_pk_bf16_f32 v150, v156, v157
	v_cvt_pk_bf16_f32 v151, v158, v159
	s_nop 1
	v_permlane32_swap_b32_e32 v148, v150
	v_permlane32_swap_b32_e32 v149, v151
	global_store_dwordx4 v[68:69], v[148:151], off offset:96
	ds_bpermute_b32 v0, v187, v64
	s_waitcnt lgkmcnt(0)
	v_add_f32_e32 v0, v64, v0
	v_div_scale_f32 v1, s[8:9], v0, v0, 1.0
	v_rcp_f32_e32 v2, v1
	s_nop 0
	v_fma_f32 v3, -v1, v2, 1.0
	v_fmac_f32_e32 v2, v3, v2
	v_div_scale_f32 v3, vcc, 1.0, v0, 1.0
	v_mul_f32_e32 v4, v3, v2
	v_fma_f32 v5, -v1, v4, v3
	v_fmac_f32_e32 v4, v5, v2
	v_fma_f32 v1, -v1, v4, v3
	v_div_fmas_f32 v1, v1, v2, v4
	v_div_fixup_f32 v4, v1, v0, 1.0
	v_lshl_add_u64 v[0:1], v[66:67], 0, v[168:169]
	v_lshl_add_u64 v[0:1], v[0:1], 0, v[176:177]
	v_mul_f32_e32 v152, v32, v4
	v_mul_f32_e32 v153, v33, v4
	v_mul_f32_e32 v154, v34, v4
	v_mul_f32_e32 v155, v35, v4
	v_mul_f32_e32 v156, v36, v4
	v_mul_f32_e32 v157, v37, v4
	v_mul_f32_e32 v158, v38, v4
	v_mul_f32_e32 v159, v39, v4
	v_cvt_pk_bf16_f32 v136, v152, v153
	v_cvt_pk_bf16_f32 v137, v154, v155
	v_cvt_pk_bf16_f32 v138, v156, v157
	v_cvt_pk_bf16_f32 v139, v158, v159
	s_nop 1
	v_permlane32_swap_b32_e32 v136, v138
	v_permlane32_swap_b32_e32 v137, v139
	global_store_dwordx4 v[0:1], v[136:139], off
	v_mul_f32_e32 v152, v40, v4
	v_mul_f32_e32 v153, v41, v4
	v_mul_f32_e32 v154, v42, v4
	v_mul_f32_e32 v155, v43, v4
	v_mul_f32_e32 v156, v44, v4
	v_mul_f32_e32 v157, v45, v4
	v_mul_f32_e32 v158, v46, v4
	v_mul_f32_e32 v159, v47, v4
	v_cvt_pk_bf16_f32 v140, v152, v153
	v_cvt_pk_bf16_f32 v141, v154, v155
	v_cvt_pk_bf16_f32 v142, v156, v157
	v_cvt_pk_bf16_f32 v143, v158, v159
	s_nop 1
	v_permlane32_swap_b32_e32 v140, v142
	v_permlane32_swap_b32_e32 v141, v143
	global_store_dwordx4 v[0:1], v[140:143], off offset:32
	v_mul_f32_e32 v152, v16, v4
	v_mul_f32_e32 v153, v17, v4
	v_mul_f32_e32 v154, v18, v4
	v_mul_f32_e32 v155, v19, v4
	v_mul_f32_e32 v156, v20, v4
	v_mul_f32_e32 v157, v21, v4
	v_mul_f32_e32 v158, v22, v4
	v_mul_f32_e32 v159, v23, v4
	v_cvt_pk_bf16_f32 v144, v152, v153
	v_cvt_pk_bf16_f32 v145, v154, v155
	v_cvt_pk_bf16_f32 v146, v156, v157
	v_cvt_pk_bf16_f32 v147, v158, v159
	s_nop 1
	v_permlane32_swap_b32_e32 v144, v146
	v_permlane32_swap_b32_e32 v145, v147
	global_store_dwordx4 v[0:1], v[144:147], off offset:64
	v_mul_f32_e32 v152, v24, v4
	v_mul_f32_e32 v153, v25, v4
	v_mul_f32_e32 v154, v26, v4
	v_mul_f32_e32 v155, v27, v4
	v_mul_f32_e32 v156, v28, v4
	v_mul_f32_e32 v157, v29, v4
	v_mul_f32_e32 v158, v30, v4
	v_mul_f32_e32 v159, v31, v4
	v_cvt_pk_bf16_f32 v148, v152, v153
	v_cvt_pk_bf16_f32 v149, v154, v155
	v_cvt_pk_bf16_f32 v150, v156, v157
	v_cvt_pk_bf16_f32 v151, v158, v159
	s_nop 1
	v_permlane32_swap_b32_e32 v148, v150
	v_permlane32_swap_b32_e32 v149, v151
	global_store_dwordx4 v[0:1], v[148:151], off offset:96
	s_barrier
